# attention: K/V prefetch via SGPR base + lane offset (no per-tile 64-bit VALU), incremental staging addresses, on-demand mask index, merged vmcnt wait, no setprio, rare no-prefetch path out of line
# baseline (speedup 1.0000x reference)
; DI void attn_s(const unsigned char* sK, int tt, int qb, int qs, int sub, int l31, int h,
;                const bf16x8 (&qf)[4], f32x16 (&O)[4], float& m, float& l, bf16x8 (&pb)[4]) {
;     ...
;     } else if (tt >= 2 * qb + 1) {
;         const int kbase = (tt - 1) * 64 + 4 * h;
; #pragma unroll
;         for (int k2 = 0; k2 < 2; ++k2)
; #pragma unroll
;             for (int i = 0; i < 16; ++i) {
;                 const int key = kbase + k2 * 32 + (i & 3) + 8 * (i >> 2);
;                 if (key > qs) st[k2][i] = -INFINITY;
;             }
;     }
; DI void attn_item(const Params& p, unsigned char* lds, int b, int hd, int qb, float lam) {
;     ...
;     const int krow_ = tid >> 4, kc_ = tid & 15, vdv_ = tid >> 3, vc_ = tid & 7;
;     const bf16_t* kp = ak + ((size_t)b * 4096 + krow_) * 1024 + hd * 128 + kc_ * 8;
;     const bf16_t* vp_ = avT + ((size_t)(b * 8 + hd) * 128 + vdv_) * 4096 + vc_ * 8;
.Lpipe_nopf_p:
	v_readfirstlane_b32 s8, v144
	v_readfirstlane_b32 s9, v145
	v_readfirstlane_b32 s100, v142
	v_readfirstlane_b32 s101, v143
	s_nop 3
	s_sub_u32 s8, s8, 0x100000
	s_subb_u32 s9, s9, 0
	s_sub_u32 s100, s100, 0x100000
	s_subb_u32 s101, s101, 0
	v_subrev_u32_e32 v144, s8, v144
	v_subrev_u32_e32 v142, s100, v142
	v_add_u32_e32 v145, 0x10000, v144
	v_add_u32_e32 v143, 0x80000, v142
	s_mul_i32 s4, s7, 0x8c00
	v_add3_u32 v232, s4, v140, v139
	v_add3_u32 v233, s4, v140, v141
	v_add3_u32 v234, s4, v150, v151
	v_add_u32_e32 v235, v234, v153
	v_add_u32_e32 v234, v234, v152
	v_add_u32_e32 v235, 0x4000, v235
	v_add_u32_e32 v234, 0x4000, v234
	s_waitcnt lgkmcnt(0)
	s_barrier
.Lpipe_loop:
	v_add3_u32 v191, s98, v156, v98
	ds_read_b128 v[172:175], v191 offset:17408
	ds_read_b128 v[176:179], v191 offset:22016
	ds_read_b128 v[180:183], v191 offset:26624
	ds_read_b128 v[192:195], v191 offset:31232
	ds_read_b128 v[200:203], v191 offset:17440
	ds_read_b128 v[204:207], v191 offset:22048
	ds_read_b128 v[208:211], v191 offset:26656
	ds_read_b128 v[212:215], v191 offset:31264
	s_add_i32 s14, s12, 0x41
	s_cmp_le_i32 s14, s0
	s_cbranch_scc1 .Lpipe_nomask_l
	s_add_i32 s14, s12, 64
	s_lshl_b32 s14, s14, 6
	v_add_u32_e32 v170, s14, v158
	v_subrev_u32_e32 v159, 59, v170
	v_cmp_gt_i32_e32 vcc, v159, v138
	s_nop 1
	v_cndmask_b32_e32 v160, v82, v188, vcc
	v_cmp_lt_i32_e32 vcc, v159, v138
	v_subrev_u32_e32 v159, 57, v170
	s_nop 0
	v_cndmask_b32_e32 v82, v160, v82, vcc
	v_cndmask_b32_e32 v83, v188, v83, vcc
	v_cmp_le_i32_e32 vcc, v159, v138
	v_subrev_u32_e32 v159, 56, v170
	s_nop 0
	v_cndmask_b32_e32 v84, v188, v84, vcc
	v_cmp_le_i32_e32 vcc, v159, v138
	v_subrev_u32_e32 v159, 51, v170
	s_nop 0
	v_cndmask_b32_e32 v85, v188, v85, vcc
	v_cmp_le_i32_e32 vcc, v159, v138
	v_subrev_u32_e32 v159, 50, v170
	s_nop 0
	v_cndmask_b32_e32 v86, v188, v86, vcc
	v_cmp_le_i32_e32 vcc, v159, v138
	v_subrev_u32_e32 v159, 49, v170
	s_nop 0
	v_cndmask_b32_e32 v87, v188, v87, vcc
	v_cmp_le_i32_e32 vcc, v159, v138
	v_subrev_u32_e32 v159, 48, v170
	s_nop 0
	v_cndmask_b32_e32 v88, v188, v88, vcc
	v_cmp_le_i32_e32 vcc, v159, v138
	v_subrev_u32_e32 v159, 43, v170
	s_nop 0
	v_cndmask_b32_e32 v89, v188, v89, vcc
	v_cmp_le_i32_e32 vcc, v159, v138
	v_subrev_u32_e32 v159, 42, v170
	s_nop 0
	v_cndmask_b32_e32 v90, v188, v90, vcc
	v_cmp_le_i32_e32 vcc, v159, v138
	v_subrev_u32_e32 v159, 41, v170
	s_nop 0
	v_cndmask_b32_e32 v91, v188, v91, vcc
	v_cmp_le_i32_e32 vcc, v159, v138
	v_subrev_u32_e32 v159, 40, v170
	s_nop 0
	v_cndmask_b32_e32 v92, v188, v92, vcc
	v_cmp_le_i32_e32 vcc, v159, v138
	v_subrev_u32_e32 v159, 35, v170
	s_nop 0
	v_cndmask_b32_e32 v93, v188, v93, vcc
	v_cmp_le_i32_e32 vcc, v159, v138
	v_subrev_u32_e32 v159, 34, v170
	s_nop 0
	v_cndmask_b32_e32 v94, v188, v94, vcc
	v_cmp_le_i32_e32 vcc, v159, v138
	v_subrev_u32_e32 v159, 33, v170
	s_nop 0
	v_cndmask_b32_e32 v95, v188, v95, vcc
	v_cmp_le_i32_e32 vcc, v159, v138
	v_subrev_u32_e32 v159, 32, v170
	s_nop 0
	v_cndmask_b32_e32 v96, v188, v96, vcc
	v_cmp_le_i32_e32 vcc, v159, v138
	v_subrev_u32_e32 v159, 27, v170
	s_nop 0
	v_cndmask_b32_e32 v97, v188, v97, vcc
	v_cmp_le_i32_e32 vcc, v159, v138
	v_subrev_u32_e32 v159, 26, v170
	s_nop 0
	v_cndmask_b32_e32 v66, v188, v66, vcc
	v_cmp_le_i32_e32 vcc, v159, v138
	v_subrev_u32_e32 v159, 25, v170
	s_nop 0
	v_cndmask_b32_e32 v67, v188, v67, vcc
	v_cmp_le_i32_e32 vcc, v159, v138
	v_subrev_u32_e32 v159, 24, v170
	s_nop 0
	v_cndmask_b32_e32 v68, v188, v68, vcc
	v_cmp_le_i32_e32 vcc, v159, v138
	v_subrev_u32_e32 v159, 19, v170
	s_nop 0
	v_cndmask_b32_e32 v69, v188, v69, vcc
	v_cmp_le_i32_e32 vcc, v159, v138
	v_subrev_u32_e32 v159, 18, v170
	s_nop 0
	v_cndmask_b32_e32 v70, v188, v70, vcc
	v_cmp_le_i32_e32 vcc, v159, v138
	v_subrev_u32_e32 v159, 17, v170
	s_nop 0
	v_cndmask_b32_e32 v71, v188, v71, vcc
	v_cmp_le_i32_e32 vcc, v159, v138
	v_add_u32_e32 v159, -16, v170
	s_nop 0
	v_cndmask_b32_e32 v72, v188, v72, vcc
	v_cmp_le_i32_e32 vcc, v159, v138
	v_add_u32_e32 v159, -11, v170
	s_nop 0
	v_cndmask_b32_e32 v73, v188, v73, vcc
	v_cmp_le_i32_e32 vcc, v159, v138
	v_add_u32_e32 v159, -10, v170
	s_nop 0
	v_cndmask_b32_e32 v74, v188, v74, vcc
	v_cmp_le_i32_e32 vcc, v159, v138
	v_add_u32_e32 v159, -9, v170
	s_nop 0
	v_cndmask_b32_e32 v75, v188, v75, vcc
	v_cmp_le_i32_e32 vcc, v159, v138
	v_add_u32_e32 v159, -8, v170
	s_nop 0
	v_cndmask_b32_e32 v76, v188, v76, vcc
	v_cmp_le_i32_e32 vcc, v159, v138
	v_add_u32_e32 v159, -3, v170
	s_nop 0
	v_cndmask_b32_e32 v77, v188, v77, vcc
	v_cmp_le_i32_e32 vcc, v159, v138
	v_add_u32_e32 v159, -2, v170
	s_nop 0
	v_cndmask_b32_e32 v78, v188, v78, vcc
	v_cmp_le_i32_e32 vcc, v159, v138
	v_add_u32_e32 v159, -1, v170
	s_nop 0
	v_cndmask_b32_e32 v79, v188, v79, vcc
	v_cmp_le_i32_e32 vcc, v159, v138
	s_nop 1
	v_cndmask_b32_e32 v80, v188, v80, vcc
	v_cmp_le_i32_e32 vcc, v170, v138
	s_nop 1
	v_cndmask_b32_e32 v81, v188, v81, vcc
; #define MFMA32(a, b, c) __builtin_amdgcn_mfma_f32_32x32x16_bf16((a), (b), (c), 0, 0, 0)
; DI unsigned pk2(float a, float b) { f32x2 v = {a, b}; return __builtin_bit_cast(unsigned, __builtin_convertvector(v, bfv2)); }
; DI void attn_s(const unsigned char* sK, int tt, int qb, int qs, int sub, int l31, int h,
;                const bf16x8 (&qf)[4], f32x16 (&O)[4], float& m, float& l, bf16x8 (&pb)[4]) {
;     ...
; #pragma unroll
;     for (int k2 = 0; k2 < 2; ++k2)
; #pragma unroll
;         for (int i = 0; i < 16; ++i) st[k2][i] = __builtin_amdgcn_exp2f(st[k2][i]);
;     {
;         const f32x16 sv = st[0] + st[1];
;         const float ps = (((sv[0] + sv[1]) + (sv[2] + sv[3])) + ((sv[4] + sv[5]) + (sv[6] + sv[7]))) + (((sv[8] + sv[9]) + (sv[10] + sv[11])) + ((sv[12] + sv[13]) + (sv[14] + sv[15])));
;         l += ps;
;     }
; #pragma unroll
;     for (int k4 = 0; k4 < 4; ++k4) {
;         const int k2 = k4 >> 1, o8 = 8 * (k4 & 1);
;         u32x4 pk;
;         pk.x = pk2(st[k2][o8 + 0], st[k2][o8 + 1]); pk.y = pk2(st[k2][o8 + 2], st[k2][o8 + 3]);
;         pk.z = pk2(st[k2][o8 + 4], st[k2][o8 + 5]); pk.w = pk2(st[k2][o8 + 6], st[k2][o8 + 7]);
;         pb[k4] = __builtin_bit_cast(bf16x8, pk);
;     }
; DI void attn_pv(const unsigned char* sV, int l31, int h, const bf16x8 (&pb)[4], f32x16 (&O)[4]) {
;     ...
;         for (int d = 0; d < 4; ++d) O[d] = MFMA32(va[d], pb[0], O[d]);
;         __builtin_amdgcn_sched_barrier(0);
; #pragma unroll
;         for (int d = 0; d < 4; ++d) va[d] = *(const bf16x8*)(vb + d * 32 * A_VROWB + 64);
;         __builtin_amdgcn_sched_barrier(0);
; #pragma unroll
;         for (int d = 0; d < 4; ++d) O[d] = MFMA32(vc[d], pb[1], O[d]);
;         __builtin_amdgcn_sched_barrier(0);
; #pragma unroll
;         for (int d = 0; d < 4; ++d) vc[d] = *(const bf16x8*)(vb + d * 32 * A_VROWB + 96);
;         __builtin_amdgcn_sched_barrier(0);
; #pragma unroll
;         for (int d = 0; d < 4; ++d) O[d] = MFMA32(va[d], pb[2], O[d]);
;         __builtin_amdgcn_sched_barrier(0);
; #pragma unroll
;         for (int d = 0; d < 4; ++d) O[d] = MFMA32(vc[d], pb[3], O[d]);
.Lpipe_nomask_l:
	v_exp_f32_e32 v82, v82
	v_exp_f32_e32 v83, v83
	v_exp_f32_e32 v84, v84
	v_exp_f32_e32 v85, v85
	v_exp_f32_e32 v86, v86
	v_exp_f32_e32 v87, v87
	v_exp_f32_e32 v88, v88
	v_exp_f32_e32 v89, v89
	v_exp_f32_e32 v90, v90
	v_exp_f32_e32 v91, v91
	v_exp_f32_e32 v92, v92
	v_exp_f32_e32 v93, v93
	v_exp_f32_e32 v94, v94
	v_exp_f32_e32 v95, v95
	v_exp_f32_e32 v96, v96
	v_exp_f32_e32 v97, v97
	v_exp_f32_e32 v66, v66
	v_exp_f32_e32 v67, v67
	v_exp_f32_e32 v68, v68
	v_exp_f32_e32 v69, v69
	v_exp_f32_e32 v70, v70
	v_exp_f32_e32 v71, v71
	v_exp_f32_e32 v72, v72
	v_exp_f32_e32 v73, v73
	v_exp_f32_e32 v74, v74
	v_exp_f32_e32 v75, v75
	v_exp_f32_e32 v76, v76
	v_exp_f32_e32 v77, v77
	v_exp_f32_e32 v78, v78
	v_exp_f32_e32 v79, v79
	v_exp_f32_e32 v80, v80
	v_exp_f32_e32 v81, v81
	v_cvt_pk_bf16_f32 v216, v82, v83
	v_cvt_pk_bf16_f32 v217, v84, v85
	v_cvt_pk_bf16_f32 v218, v86, v87
	v_cvt_pk_bf16_f32 v219, v88, v89
	v_cvt_pk_bf16_f32 v220, v90, v91
	v_cvt_pk_bf16_f32 v221, v92, v93
	v_cvt_pk_bf16_f32 v222, v94, v95
	v_cvt_pk_bf16_f32 v223, v96, v97
	v_cvt_pk_bf16_f32 v224, v66, v67
	v_cvt_pk_bf16_f32 v225, v68, v69
	v_cvt_pk_bf16_f32 v226, v70, v71
	v_cvt_pk_bf16_f32 v227, v72, v73
	v_cvt_pk_bf16_f32 v228, v74, v75
	v_cvt_pk_bf16_f32 v229, v76, v77
	v_cvt_pk_bf16_f32 v230, v78, v79
	v_cvt_pk_bf16_f32 v231, v80, v81
	v_add_f32_e32 v160, v82, v66
	v_add_f32_e32 v161, v83, v67
	v_add_f32_e32 v162, v84, v68
	v_add_f32_e32 v163, v85, v69
	v_add_f32_e32 v164, v86, v70
	v_add_f32_e32 v165, v87, v71
	v_add_f32_e32 v166, v88, v72
	v_add_f32_e32 v167, v89, v73
	v_add_f32_e32 v168, v90, v74
	v_add_f32_e32 v169, v91, v75
	v_add_f32_e32 v170, v92, v76
	v_add_f32_e32 v171, v93, v77
	v_add_f32_e32 v196, v94, v78
	v_add_f32_e32 v197, v95, v79
	v_add_f32_e32 v198, v96, v80
	v_add_f32_e32 v199, v97, v81
	s_mov_b32 s14, 0x43800000
	v_add_f32_e32 v160, v160, v168
	v_add_f32_e32 v161, v161, v169
	v_add_f32_e32 v162, v162, v170
	v_add_f32_e32 v163, v163, v171
	v_add_f32_e32 v164, v164, v196
	v_add_f32_e32 v165, v165, v197
	v_add_f32_e32 v166, v166, v198
	v_add_f32_e32 v167, v167, v199
	v_add_f32_e32 v160, v160, v164
	v_add_f32_e32 v161, v161, v165
	v_add_f32_e32 v162, v162, v166
	v_add_f32_e32 v163, v163, v167
	v_add_f32_e32 v160, v160, v162
	v_add_f32_e32 v161, v161, v163
	v_add_f32_e32 v159, v160, v161
	v_cmp_lt_f32_e32 vcc, s14, v159
	s_cbranch_vccnz .Lpipe_rare
.Lpipe_rejoin:
	v_add_f32_e32 v1, v1, v159
	s_add_u32 s8, s8, 0x20000
	s_addc_u32 s9, s9, 0
	s_add_u32 s100, s100, 0x80
	s_addc_u32 s101, s101, 0
	s_mov_b32 s13, s7
	s_mul_i32 s98, s7, 0x8c00
	s_add_i32 s4, s7, 1
	s_cmp_lg_u32 s7, 2
	s_cselect_b32 s7, s4, 0
	s_mul_i32 s4, s7, 0x8c00
	v_add3_u32 v237, s98, v155, v154
	s_sub_i32 s14, s4, s98
	v_add_u32_e32 v232, s14, v232
	v_add_u32_e32 v233, s14, v233
	v_add_u32_e32 v234, s14, v234
	v_add_u32_e32 v235, s14, v235
	s_add_i32 s12, s12, 1
	s_cmp_eq_u32 s11, s12
	s_cbranch_scc1 .Lpipe_final
	s_barrier
	ds_read_b128 v[160:163], v237
	ds_read_b128 v[164:167], v237 offset:32
	ds_read_b128 v[168:171], v237 offset:8704
	ds_read_b128 v[196:199], v237 offset:8736
	s_waitcnt lgkmcnt(8)
	v_mfma_f32_32x32x16_bf16 v[50:65], v[172:175], v[216:219], v[50:65]
	ds_read_b128 v[172:175], v237 offset:64
	v_mfma_f32_32x32x16_bf16 v[34:49], v[176:179], v[216:219], v[34:49]
	ds_read_b128 v[176:179], v237 offset:96
	v_mfma_f32_32x32x16_bf16 v[18:33], v[180:183], v[216:219], v[18:33]
	ds_read_b128 v[180:183], v237 offset:8768
	v_mfma_f32_32x32x16_bf16 v[2:17], v[192:195], v[216:219], v[2:17]
	ds_read_b128 v[192:195], v237 offset:8800
	s_waitcnt lgkmcnt(8)
	v_mfma_f32_32x32x16_bf16 v[50:65], v[200:203], v[220:223], v[50:65]
	ds_read_b128 v[200:203], v191 offset:17472
	v_mfma_f32_32x32x16_bf16 v[34:49], v[204:207], v[220:223], v[34:49]
	ds_read_b128 v[204:207], v191 offset:22080
	v_mfma_f32_32x32x16_bf16 v[18:33], v[208:211], v[220:223], v[18:33]
	ds_read_b128 v[208:211], v191 offset:26688
	v_mfma_f32_32x32x16_bf16 v[2:17], v[212:215], v[220:223], v[2:17]
	ds_read_b128 v[212:215], v191 offset:31296
	s_waitcnt lgkmcnt(8)
	v_mfma_f32_32x32x16_bf16 v[82:97], v[160:163], v[100:103], v[240:255]
	ds_read_b128 v[160:163], v191 offset:17504
	v_mfma_f32_32x32x16_bf16 v[66:81], v[168:171], v[100:103], v[240:255]
	ds_read_b128 v[168:171], v191 offset:26720
	v_mfma_f32_32x32x16_bf16 v[82:97], v[164:167], v[104:107], v[82:97]
	ds_read_b128 v[164:167], v191 offset:22112
	v_mfma_f32_32x32x16_bf16 v[66:81], v[196:199], v[104:107], v[66:81]
	ds_read_b128 v[196:199], v191 offset:31328
	s_waitcnt lgkmcnt(8)
	v_mfma_f32_32x32x16_bf16 v[82:97], v[172:175], v[108:111], v[82:97]
	s_waitcnt vmcnt(0)
	ds_write_b128 v232, v[116:119]
	v_mfma_f32_32x32x16_bf16 v[66:81], v[180:183], v[108:111], v[66:81]
	ds_write_b128 v233, v[120:123]
	v_mfma_f32_32x32x16_bf16 v[82:97], v[176:179], v[112:115], v[82:97]
	ds_write2_b64 v234, v[124:125], v[126:127] offset0:128 offset1:130
	v_mfma_f32_32x32x16_bf16 v[66:81], v[192:195], v[112:115], v[66:81]
	ds_write2_b64 v235, v[128:129], v[130:131] offset0:128 offset1:130
	s_add_i32 s14, s12, 0x43
	s_cmp_ge_i32 s14, s6
	s_cbranch_scc1 .Lpipe_k2_nopf
	s_waitcnt lgkmcnt(8)
	v_mfma_f32_32x32x16_bf16 v[50:65], v[200:203], v[224:227], v[50:65]
	global_load_dwordx4 v[116:119], v144, s[8:9]
	v_mfma_f32_32x32x16_bf16 v[34:49], v[204:207], v[224:227], v[34:49]
	global_load_dwordx4 v[120:123], v145, s[8:9]
	v_mfma_f32_32x32x16_bf16 v[18:33], v[208:211], v[224:227], v[18:33]
	global_load_dwordx4 v[124:127], v142, s[100:101]
	v_mfma_f32_32x32x16_bf16 v[2:17], v[212:215], v[224:227], v[2:17]
	global_load_dwordx4 v[128:131], v143, s[100:101]
.Lpipe_k3:
	s_waitcnt lgkmcnt(4)
	v_mfma_f32_32x32x16_bf16 v[50:65], v[160:163], v[228:231], v[50:65]
	v_mfma_f32_32x32x16_bf16 v[34:49], v[164:167], v[228:231], v[34:49]
	v_mfma_f32_32x32x16_bf16 v[18:33], v[168:171], v[228:231], v[18:33]
	v_mfma_f32_32x32x16_bf16 v[2:17], v[196:199], v[228:231], v[2:17]
	s_waitcnt lgkmcnt(0)
	s_barrier
	s_branch .Lpipe_loop

; #define MFMA32(a, b, c) __builtin_amdgcn_mfma_f32_32x32x16_bf16((a), (b), (c), 0, 0, 0)
; DI void attn_pv(const unsigned char* sV, int l31, int h, const bf16x8 (&pb)[4], f32x16 (&O)[4]) {
;     ...
;         for (int d = 0; d < 4; ++d) O[d] = MFMA32(va[d], pb[0], O[d]);
;         __builtin_amdgcn_sched_barrier(0);
; #pragma unroll
;         for (int d = 0; d < 4; ++d) va[d] = *(const bf16x8*)(vb + d * 32 * A_VROWB + 64);
;         __builtin_amdgcn_sched_barrier(0);
; #pragma unroll
;         for (int d = 0; d < 4; ++d) O[d] = MFMA32(vc[d], pb[1], O[d]);
;         __builtin_amdgcn_sched_barrier(0);
; #pragma unroll
;         for (int d = 0; d < 4; ++d) vc[d] = *(const bf16x8*)(vb + d * 32 * A_VROWB + 96);
;         __builtin_amdgcn_sched_barrier(0);
; #pragma unroll
;         for (int d = 0; d < 4; ++d) O[d] = MFMA32(va[d], pb[2], O[d]);
;         __builtin_amdgcn_sched_barrier(0);
; #pragma unroll
;         for (int d = 0; d < 4; ++d) O[d] = MFMA32(vc[d], pb[3], O[d]);
.Lpipe_k2_nopf:
	s_waitcnt lgkmcnt(8)
	v_mfma_f32_32x32x16_bf16 v[50:65], v[200:203], v[224:227], v[50:65]
	v_mfma_f32_32x32x16_bf16 v[34:49], v[204:207], v[224:227], v[34:49]
	v_mfma_f32_32x32x16_bf16 v[18:33], v[208:211], v[224:227], v[18:33]
	v_mfma_f32_32x32x16_bf16 v[2:17], v[212:215], v[224:227], v[2:17]
	s_branch .Lpipe_k3

; #define LAS __attribute__((address_space(3)))
; #define GRID_BARRIER() { XcdBarrier xb_; xb_.bar = (unsigned*)(p.ws + OFF_XBAR); xb_.x = xb_xcc_id(); xb_.st = (volatile LAS unsigned*)(lds + LDS_ITEM + 16); xcd_barrier(xb_); }
; __global__ void __launch_bounds__(512) hybrid_fwd(Params p) {
;     extern __shared__ __attribute__((aligned(16))) unsigned char lds[];
;     ...
;     run_phase(p, lds, p.phase_lo);
;     ...
;     cg::grid_group grid = cg::this_grid();
;     if (p.phase_lo == 77) grid.sync();
;     {
;         volatile LAS unsigned* st = (volatile LAS unsigned*)(lds + LDS_ITEM + 16);
;         if (threadIdx.x == 0) { st[0] = 0u; st[1] = 0u; }
;         __syncthreads();
;         (void)xcd_barrier_post((unsigned*)(p.ws + OFF_XBAR), st);
;     }
;     ...
;     phase0(p, lds); GRID_BARRIER();
;     phase1(p, lds); GRID_BARRIER();
;     phase15(p, lds); GRID_BARRIER();
;     phase2(p, lds); GRID_BARRIER();
;     phase3(p, lds); GRID_BARRIER();
;     phase4(p, lds);
;     ...
; }
	.amdhsa_kernel _Z10hybrid_fwd6Params
		.amdhsa_group_segment_fixed_size 0
		.amdhsa_private_segment_fixed_size 0
		.amdhsa_kernarg_size 408
		.amdhsa_user_sgpr_count 2
		.amdhsa_user_sgpr_dispatch_ptr 0
		.amdhsa_user_sgpr_queue_ptr 0
		.amdhsa_user_sgpr_kernarg_segment_ptr 1
		.amdhsa_user_sgpr_dispatch_id 0
		.amdhsa_user_sgpr_kernarg_preload_length 0
		.amdhsa_user_sgpr_kernarg_preload_offset 0
		.amdhsa_user_sgpr_private_segment_size 0
		.amdhsa_uses_dynamic_stack 0
		.amdhsa_enable_private_segment 0
		.amdhsa_system_sgpr_workgroup_id_x 1
		.amdhsa_system_sgpr_workgroup_id_y 0
		.amdhsa_system_sgpr_workgroup_id_z 0
		.amdhsa_system_sgpr_workgroup_info 0
		.amdhsa_system_vgpr_workitem_id 2
		.amdhsa_next_free_vgpr 256
		.amdhsa_next_free_sgpr 102
		.amdhsa_accum_offset 256
		.amdhsa_reserve_vcc 1
		.amdhsa_float_round_mode_32 0
		.amdhsa_float_round_mode_16_64 0
		.amdhsa_float_denorm_mode_32 3
		.amdhsa_float_denorm_mode_16_64 3
		.amdhsa_dx10_clamp 1
		.amdhsa_ieee_mode 1
		.amdhsa_fp16_overflow 0
		.amdhsa_tg_split 0
		.amdhsa_exception_fp_ieee_invalid_op 0
		.amdhsa_exception_fp_denorm_src 0
		.amdhsa_exception_fp_ieee_div_zero 0
		.amdhsa_exception_fp_ieee_overflow 0
		.amdhsa_exception_fp_ieee_underflow 0
		.amdhsa_exception_fp_ieee_inexact 0
		.amdhsa_exception_int_div_zero 0
	.end_amdhsa_kernel

; #define LAS __attribute__((address_space(3)))
; #define GRID_BARRIER() { XcdBarrier xb_; xb_.bar = (unsigned*)(p.ws + OFF_XBAR); xb_.x = xb_xcc_id(); xb_.st = (volatile LAS unsigned*)(lds + LDS_ITEM + 16); xcd_barrier(xb_); }
; __global__ void __launch_bounds__(512) hybrid_fwd(Params p) {
;     extern __shared__ __attribute__((aligned(16))) unsigned char lds[];
;     ...
;     run_phase(p, lds, p.phase_lo);
;     ...
;     cg::grid_group grid = cg::this_grid();
;     if (p.phase_lo == 77) grid.sync();
;     {
;         volatile LAS unsigned* st = (volatile LAS unsigned*)(lds + LDS_ITEM + 16);
;         if (threadIdx.x == 0) { st[0] = 0u; st[1] = 0u; }
;         __syncthreads();
;         (void)xcd_barrier_post((unsigned*)(p.ws + OFF_XBAR), st);
;     }
;     ...
;     phase0(p, lds); GRID_BARRIER();
;     phase1(p, lds); GRID_BARRIER();
;     phase15(p, lds); GRID_BARRIER();
;     phase2(p, lds); GRID_BARRIER();
;     phase3(p, lds); GRID_BARRIER();
;     phase4(p, lds);
;     ...
; }
amdhsa.kernels:
  - .agpr_count:     0
    .args:
      - .offset:         0
        .size:           152
        .value_kind:     by_value
      - .offset:         152
        .size:           4
        .value_kind:     hidden_block_count_x
      - .offset:         156
        .size:           4
        .value_kind:     hidden_block_count_y
      - .offset:         160
        .size:           4
        .value_kind:     hidden_block_count_z
      - .offset:         164
        .size:           2
        .value_kind:     hidden_group_size_x
      - .offset:         166
        .size:           2
        .value_kind:     hidden_group_size_y
      - .offset:         168
        .size:           2
        .value_kind:     hidden_group_size_z
      - .offset:         170
        .size:           2
        .value_kind:     hidden_remainder_x
      - .offset:         172
        .size:           2
        .value_kind:     hidden_remainder_y
      - .offset:         174
        .size:           2
        .value_kind:     hidden_remainder_z
      - .offset:         192
        .size:           8
        .value_kind:     hidden_global_offset_x
      - .offset:         200
        .size:           8
        .value_kind:     hidden_global_offset_y
      - .offset:         208
        .size:           8
        .value_kind:     hidden_global_offset_z
      - .offset:         216
        .size:           2
        .value_kind:     hidden_grid_dims
      - .offset:         240
        .size:           8
        .value_kind:     hidden_multigrid_sync_arg
      - .offset:         272
        .size:           4
        .value_kind:     hidden_dynamic_lds_size
    .group_segment_fixed_size: 0
    .kernarg_segment_align: 8
    .kernarg_segment_size: 408
    .language:       OpenCL C
    .language_version:
      - 2
      - 0
    .max_flat_workgroup_size: 512
    .name:           _Z10hybrid_fwd6Params
    .private_segment_fixed_size: 0
    .sgpr_count:     108
    .sgpr_spill_count: 39
    .symbol:         _Z10hybrid_fwd6Params.kd
    .uniform_work_group_size: 1
    .uses_dynamic_stack: false
    .vgpr_count:     256
    .vgpr_spill_count: 0
    .wavefront_size: 64
